# early L2 write-back issued by an early-arriving workgroup at the two full seams after the mixer in-projection
# speedup vs baseline: 1.0093x; 1.0042x over previous
; __device__ __forceinline__ void xcd_barrier(const XcdBarrier& b) {
;     asm volatile("s_waitcnt vmcnt(0)" ::: "memory");
;     __syncthreads();
;     if (threadIdx.x == 0) {
;         unsigned* bar = b.bar;
;         __builtin_amdgcn_s_waitcnt(0);
;         unsigned nloc = b.st[0], nx = b.st[1];
;         if (nloc == 0u) { xcd_barrier_complete(bar, b.x, nloc, nx); b.st[0] = nloc; b.st[1] = nx; }
.LBB0_622:
	s_cmp_lt_i32 s92, 5
	s_cselect_b64 s[80:81], -1, 0
	s_cmp_gt_i32 s93, 4
	s_cselect_b64 s[0:1], -1, 0
	s_and_b64 s[0:1], s[80:81], s[0:1]
	s_andn2_b64 vcc, exec, s[0:1]
	s_cbranch_vccnz .LBB0_704
	s_andn2_b64 vcc, exec, s[10:11]
	s_cbranch_vccnz .LBB0_673
	s_waitcnt vmcnt(0)
	v_cmp_eq_u32_e32 vcc, 0, v254
	s_waitcnt vmcnt(0) lgkmcnt(0)
	s_barrier
	s_and_saveexec_b64 s[0:1], vcc
	s_cbranch_execz .LBB0_672
	s_lshr_b32 s3, s2, 3
	s_cmp_eq_u32 s3, 31
	s_cbranch_scc0 .Lnofl_4
	buffer_wbl2 sc1

; __device__ __forceinline__ void xcd_barrier(const XcdBarrier& b) {
;     asm volatile("s_waitcnt vmcnt(0)" ::: "memory");
;     __syncthreads();
;     if (threadIdx.x == 0) {
;         unsigned* bar = b.bar;
;         __builtin_amdgcn_s_waitcnt(0);
;         unsigned nloc = b.st[0], nx = b.st[1];
;         if (nloc == 0u) { xcd_barrier_complete(bar, b.x, nloc, nx); b.st[0] = nloc; b.st[1] = nx; }
.LBB0_1504:
	s_cmp_lt_i32 s92, 14
	s_cselect_b64 s[46:47], -1, 0
	s_cmp_gt_i32 s93, 13
	s_cselect_b64 s[0:1], -1, 0
	s_and_b64 s[0:1], s[46:47], s[0:1]
	s_andn2_b64 vcc, exec, s[0:1]
	s_cbranch_vccnz .LBB0_1587
	s_andn2_b64 vcc, exec, s[10:11]
	s_cbranch_vccnz .LBB0_1555
	s_waitcnt vmcnt(0)
	v_cmp_eq_u32_e32 vcc, 0, v254
	s_waitcnt vmcnt(0) lgkmcnt(0)
	s_barrier
	s_and_saveexec_b64 s[0:1], vcc
	s_cbranch_execz .LBB0_1554
	s_lshr_b32 s3, s2, 3
	s_cmp_eq_u32 s3, 31
	s_cbranch_scc0 .Lnofl_13
	buffer_wbl2 sc1
